# work-queue pop: next item index fetched one item ahead by thread 0 (atomic issued at the previous pop)
# speedup vs baseline: 1.0076x; 1.0018x over previous
.LBB0_135:
	s_or_b64 exec, exec, s[0:1]
	v_readlane_b32 s6, v245, 61
	s_lshl_b32 s16, s6, 6
	v_readlane_b32 s68, v245, 20
	s_lshl_b64 s[0:1], s[16:17], 2
	v_readlane_b32 s80, v245, 32
	v_readlane_b32 s81, v245, 33
	s_add_u32 s0, s80, s0
	s_addc_u32 s1, s81, s1
	v_writelane_b32 v244, s0, 24
	s_lshl_b32 s16, s6, 12
	s_lshl_b32 s14, s6, 10
	v_writelane_b32 v244, s1, 25
	s_lshl_b64 s[0:1], s[16:17], 2
	s_add_u32 s88, s84, s0
	s_mov_b32 s15, s17
	v_readlane_b32 s69, v245, 21
	v_readlane_b32 s70, v245, 22
	v_readlane_b32 s71, v245, 23
	v_readlane_b32 s72, v245, 24
	v_readlane_b32 s73, v245, 25
	v_readlane_b32 s74, v245, 26
	v_readlane_b32 s75, v245, 27
	v_readlane_b32 s76, v245, 28
	v_readlane_b32 s77, v245, 29
	v_readlane_b32 s78, v245, 30
	v_readlane_b32 s79, v245, 31
	v_readlane_b32 s82, v245, 34
	v_readlane_b32 s83, v245, 35
	s_addc_u32 s89, s85, s1
	s_lshl_b64 s[2:3], s[14:15], 2
	s_add_u32 s28, s86, s2
	v_readlane_b32 s68, v245, 2
	s_addc_u32 s29, s87, s3
	v_readlane_b32 s78, v245, 12
	v_readlane_b32 s79, v245, 13
	s_add_u32 s18, s78, s0
	s_addc_u32 s19, s79, s1
	s_lshl_b32 s22, s6, 8
	v_readlane_b32 s69, v245, 3
	v_readlane_b32 s70, v245, 4
	v_readlane_b32 s71, v245, 5
	v_readlane_b32 s72, v245, 6
	v_readlane_b32 s73, v245, 7
	v_readlane_b32 s74, v245, 8
	v_readlane_b32 s75, v245, 9
	v_readlane_b32 s76, v245, 10
	v_readlane_b32 s77, v245, 11
	v_readlane_b32 s80, v245, 14
	v_readlane_b32 s81, v245, 15
	v_readlane_b32 s82, v245, 16
	v_readlane_b32 s83, v245, 17
	s_and_saveexec_b64 s[0:1], s[4:5]
	s_cbranch_execz .Lqp_skipA
	v_readlane_b32 s6, v244, 24
	v_readlane_b32 s7, v244, 25
	v_mov_b32_e32 v175, 1
	s_nop 4
	global_atomic_add v174, v179, v175, s[6:7] offset:2560 sc0
	s_waitcnt vmcnt(0)
.Lqp_skipA:
	s_or_b64 exec, exec, s[0:1]
	s_branch .LBB0_139

.LBB0_139:
	s_waitcnt lgkmcnt(0)
	s_barrier
	s_and_saveexec_b64 s[0:1], s[4:5]
	s_cbranch_execz .LBB0_143
	v_readlane_b32 s6, v244, 24
	v_readlane_b32 s7, v244, 25
	s_waitcnt vmcnt(8)
	v_mov_b32_e32 v0, v174
	v_mov_b32_e32 v175, 1
	s_nop 0
	ds_write_b32 v219, v0
	s_nop 1
	global_atomic_add v174, v179, v175, s[6:7] offset:2560 sc0

.LBB0_240:
	s_or_b64 exec, exec, s[0:1]
	v_readlane_b32 s0, v245, 61
	s_lshl_b32 s16, s0, 9
	v_readlane_b32 s68, v245, 2
	s_lshl_b64 s[0:1], s[16:17], 2
	v_readlane_b32 s82, v245, 16
	v_readlane_b32 s83, v245, 17
	s_add_u32 s0, s82, s0
	v_writelane_b32 v244, s0, 26
	s_addc_u32 s0, s83, s1
	s_barrier
	v_readlane_b32 s69, v245, 3
	v_readlane_b32 s70, v245, 4
	v_readlane_b32 s71, v245, 5
	v_readlane_b32 s72, v245, 6
	v_readlane_b32 s73, v245, 7
	v_readlane_b32 s74, v245, 8
	v_readlane_b32 s75, v245, 9
	v_readlane_b32 s76, v245, 10
	v_readlane_b32 s77, v245, 11
	v_readlane_b32 s78, v245, 12
	v_readlane_b32 s79, v245, 13
	v_readlane_b32 s80, v245, 14
	v_readlane_b32 s81, v245, 15
	v_writelane_b32 v244, s0, 27
	s_and_saveexec_b64 s[0:1], s[4:5]
	s_cbranch_execz .Lqp_skipB
	v_readlane_b32 s6, v244, 24
	v_readlane_b32 s7, v244, 25
	v_mov_b32_e32 v175, 1
	s_nop 4
	global_atomic_add v174, v179, v175, s[6:7] offset:2688 sc0
	s_waitcnt vmcnt(0)

.LBB0_244:
	s_barrier
	s_and_saveexec_b64 s[0:1], s[4:5]
	s_cbranch_execz .LBB0_248
	v_readlane_b32 s6, v244, 24
	v_readlane_b32 s7, v244, 25
	s_waitcnt vmcnt(8)
	v_mov_b32_e32 v0, v174
	v_mov_b32_e32 v175, 1
	s_nop 0
	ds_write_b32 v219, v0
	s_nop 1
	global_atomic_add v174, v179, v175, s[6:7] offset:2688 sc0
